# attention near-tile path: redundant 24-state MFMA pad removed, bias table values loaded straight into destination/temp registers (no v_mov shuffles, 3 waits), identity add folded
# speedup vs baseline: 1.0084x; 1.0008x over previous
; #define SBAR() __builtin_amdgcn_sched_barrier(0)
; #define VRD(i) do { if constexpr (VAR & 2) break; lo[(i) & 3] = vtr(vb + v_rd_off((i) >> 2, (i) & 3, 0)); hv[(i) & 3] = vtr(vb + v_rd_off((i) >> 2, (i) & 3, 1)); } while (0)
; template <int VAR> ...
;     ...
;     float ps = 0.f;
;     if constexpr (VAR & 4) { ka[0] = qr[0]; ka[1] = qr[1]; ka[2] = qr[2]; ka[3] = qr[3]; kb[0] = qr[0]; kb[1] = qr[1]; kb[2] = qr[2]; kb[3] = qr[3]; }
;     ka[0] = kp[0]; kb[0] = kp[1]; ka[1] = kp[2]; kb[1] = kp[3]; if (dk) glds16(gk, lk); SBAR();
;     { const f32x16 z = f32x16{};
;       QKM(x0, ka[0], qr[0], z);  SUM4(y0, 0); PKA(y0, 0);       SBAR();
;       QKM(x1, kb[0], qr[0], z);  SUM4(y0, 4); PKB(y0, 4, pa0);  KRD(2); if (dv) glds16(gv, lv); SBAR(); }
;     QKM(x0, ka[1], qr[1], x0); SUM4(y0, 8); PKA(y0, 8);       SBAR();
;     QKM(x1, kb[1], qr[1], x1); SUM4(y0, 12); PKB(y0, 12, pa1); KRD(3); if (dv) glds16(gv + 8192, lv + 8192); SBAR();
;     QKM(x0, ka[2], qr[2], x0); SUM4(y1, 0); PKA(y1, 0);       SBAR();
;     QKM(x1, kb[2], qr[2], x1); SUM4(y1, 4); PKB(y1, 4, pa2);  SBAR();
;     QKM(x0, ka[3], qr[3], x0); SUM4(y1, 8); PKA(y1, 8);       SBAR();
;     QKM(x1, kb[3], qr[3], x1); SUM4(y1, 12); PKB(y1, 12, pa3); VRD(0); VRD(1); SBAR();
;     VRD(2); VRD(3); SBAR();
;     if (near) {
;         float tA[4], uA[4], tB[4], uB[4];
;     ...
;         TLD(tA, uA, 0); SBAR(); TLD(tB, uB, 1); SBAR();
;         asm volatile("s_nop 15\n\ts_nop 7" : "+v"(x0), "+v"(x1));
;         TAD(tA, uA, 0); SBAR(); TLD(tA, uA, 2); SBAR(); TAD(tB, uB, 1); SBAR(); TLD(tB, uB, 3); SBAR(); TAD(tA, uA, 2); SBAR(); TAD(tB, uB, 3);
;     ...
;     } else if (__builtin_expect(shift != 0.f, 0)) {
;         asm volatile("s_nop 15\n\ts_nop 7" : "+v"(x0), "+v"(x1));
; #pragma unroll
;         for (int r = 0; r < 16; ++r) { asm volatile("v_sub_f32 %0, %0, %1" : "+v"(x0[r]) : "v"(shift)); asm volatile("v_sub_f32 %0, %0, %1" : "+v"(x1[r]) : "v"(shift)); }
;     }
;     SBAR();
;     ...
;     GAPB(0, pa0); GAPB(1, pa1); GAPB(2, pa2); GAPB(3, pa3); GAPB(4, pa0); GAPB(5, pa1); GAPB(6, pa2); GAPB(7, pa3);
;     GAPB(8, pa0); GAPB(9, pa1); GAPB(10, pa2); GAPB(11, pa3);
;     if (wv == 3) asm volatile("s_waitcnt vmcnt(3)" ::: "memory"); else if (wv == 2) asm volatile("s_waitcnt vmcnt(2)" ::: "memory"); else asm volatile("s_waitcnt vmcnt(0)" ::: "memory");
;     asm volatile("s_waitcnt lgkmcnt(0)\n\ts_barrier" ::: "memory");
.LBB0_356:
	s_lshl_b32 s0, s67, 13
	s_lshl_b32 s1, s86, 14
	s_add_i32 s90, s20, 1
	s_add_i32 s0, s0, s88
	s_add_i32 s66, s1, s87
	v_lshl_add_u64 v[4:5], v[206:207], 0, s[44:45]
	s_mov_b32 m0, s0
	s_lshl_b32 s92, s91, 13
	global_load_lds_dwordx4 v[4:5], off
	v_add_u32_e32 v12, s92, v215
	s_waitcnt lgkmcnt(3)
	v_mfma_f32_32x32x16_bf16 v[130:145], v[174:177], v[146:149], 0
	v_add_f32_e32 v4, v82, v83
	v_add_f32_e32 v5, v84, v85
	v_add_f32_e32 v6, v4, v5
	v_cvt_pk_bf16_f32 v4, v82, v83
	v_cvt_pk_bf16_f32 v5, v84, v85
	v_add_f32_e32 v7, v86, v87
	v_add_f32_e32 v8, v88, v89
	s_waitcnt lgkmcnt(2)
	v_mfma_f32_32x32x16_bf16 v[114:129], v[170:173], v[146:149], 0
	v_add_f32_e32 v7, v7, v8
	v_add_f32_e32 v8, v7, v6
	v_cvt_pk_bf16_f32 v6, v86, v87
	v_cvt_pk_bf16_f32 v7, v88, v89
	v_add_u32_e32 v9, v12, v218
	s_mov_b32 m0, s66
	ds_read_b128 v[14:17], v9 offset:49152
	ds_read_b128 v[86:89], v9 offset:53248
	global_load_lds_dwordx4 v[208:209], off
	s_waitcnt lgkmcnt(3)
	v_mfma_f32_32x32x16_bf16 v[130:145], v[166:169], v[150:153], v[130:145]
	v_add_f32_e32 v9, v90, v91
	v_add_f32_e32 v10, v92, v93
	v_add_f32_e32 v9, v9, v10
	v_add_f32_e32 v10, v9, v8
	v_cvt_pk_bf16_f32 v8, v90, v91
	v_cvt_pk_bf16_f32 v9, v92, v93
	v_add_f32_e32 v11, v94, v95
	v_add_f32_e32 v13, v96, v97
	s_waitcnt lgkmcnt(2)
	v_mfma_f32_32x32x16_bf16 v[114:129], v[162:165], v[150:153], v[114:129]
	v_add_f32_e32 v11, v11, v13
	v_add_f32_e32 v13, v11, v10
	v_cvt_pk_bf16_f32 v10, v94, v95
	v_cvt_pk_bf16_f32 v11, v96, v97
	v_add_u32_e32 v12, v12, v219
	ds_read_b128 v[90:93], v12 offset:49152
	ds_read_b128 v[82:85], v12 offset:53248
	s_add_i32 m0, s66, 0x2000
	v_lshl_add_u64 v[94:95], v[208:209], 0, s[22:23]
	global_load_lds_dwordx4 v[94:95], off
	s_lshl_b32 s2, s67, 14
	s_sub_i32 s66, s89, 64
	s_cmp_le_i32 s66, s85
	s_waitcnt lgkmcnt(3)
	v_mfma_f32_32x32x16_bf16 v[130:145], v[14:17], v[154:157], v[130:145]
	v_add_f32_e32 v12, v98, v99
	v_add_f32_e32 v94, v100, v101
	v_add_f32_e32 v12, v12, v94
	v_add_f32_e32 v94, v12, v13
	v_cvt_pk_bf16_f32 v12, v98, v99
	v_cvt_pk_bf16_f32 v13, v100, v101
	s_waitcnt lgkmcnt(2)
	v_mfma_f32_32x32x16_bf16 v[114:129], v[86:89], v[154:157], v[114:129]
	v_add_f32_e32 v14, v102, v103
	v_add_f32_e32 v15, v104, v105
	v_add_f32_e32 v14, v14, v15
	v_add_f32_e32 v16, v14, v94
	v_cvt_pk_bf16_f32 v14, v102, v103
	v_cvt_pk_bf16_f32 v15, v104, v105
	s_waitcnt lgkmcnt(1)
	v_mfma_f32_32x32x16_bf16 v[130:145], v[90:93], v[158:161], v[130:145]
	v_add_f32_e32 v17, v106, v107
	v_add_f32_e32 v86, v108, v109
	v_add_f32_e32 v17, v17, v86
	v_add_f32_e32 v16, v17, v16
	v_cvt_pk_bf16_f32 v178, v106, v107
	v_cvt_pk_bf16_f32 v179, v108, v109
	v_add_f32_e32 v17, v110, v111
	v_add_f32_e32 v86, v112, v113
	v_add_f32_e32 v17, v17, v86
	v_add_f32_e32 v229, v17, v16
	v_cvt_pk_bf16_f32 v180, v110, v111
	v_cvt_pk_bf16_f32 v181, v112, v113
	v_add_u32_e32 v16, s2, v214
	s_waitcnt lgkmcnt(0)
	v_mfma_f32_32x32x16_bf16 v[114:129], v[82:85], v[158:161], v[114:129]
	ds_read_b64_tr_b16 v[174:175], v16
	ds_read_b64_tr_b16 v[176:177], v16 offset:256
	ds_read_b64_tr_b16 v[170:171], v16 offset:4096
	ds_read_b64_tr_b16 v[172:173], v16 offset:4352
	ds_read_b64_tr_b16 v[166:167], v16 offset:8192
	ds_read_b64_tr_b16 v[168:169], v16 offset:8448
	ds_read_b64_tr_b16 v[162:163], v16 offset:12288
	ds_read_b64_tr_b16 v[164:165], v16 offset:12544
	s_cbranch_scc0 .LBB0_396
	v_mov_b64_e32 v[82:83], v[130:131]
	s_and_b64 vcc, exec, s[4:5]
	v_mov_b64_e32 v[84:85], v[132:133]
	v_mov_b64_e32 v[86:87], v[134:135]
	v_mov_b64_e32 v[88:89], v[136:137]
	v_mov_b64_e32 v[90:91], v[138:139]
	v_mov_b64_e32 v[92:93], v[140:141]
	v_mov_b64_e32 v[94:95], v[142:143]
	v_mov_b64_e32 v[96:97], v[144:145]
	s_cbranch_vccnz .Lp2t_shift1
.LBB0_367:
	s_waitcnt lgkmcnt(6)
	v_mfma_f32_32x32x16_bf16 v[66:81], v[4:7], v[174:177], v[66:81]
	v_exp_f32_e32 v82, v82
	v_exp_f32_e32 v114, v114
	ds_read_b64_tr_b16 v[98:99], v16 offset:512
	ds_read_b64_tr_b16 v[100:101], v16 offset:768
	s_waitcnt lgkmcnt(6)
	v_mfma_f32_32x32x16_bf16 v[66:81], v[8:11], v[170:173], v[66:81]
	v_exp_f32_e32 v83, v83
	v_exp_f32_e32 v115, v115
	ds_read_b64_tr_b16 v[102:103], v16 offset:4608
	ds_read_b64_tr_b16 v[104:105], v16 offset:4864
	s_waitcnt lgkmcnt(6)
	v_mfma_f32_32x32x16_bf16 v[66:81], v[12:15], v[166:169], v[66:81]
	v_exp_f32_e32 v84, v84
	v_exp_f32_e32 v116, v116
	ds_read_b64_tr_b16 v[106:107], v16 offset:8704
	ds_read_b64_tr_b16 v[108:109], v16 offset:8960
	s_waitcnt lgkmcnt(6)
	v_mfma_f32_32x32x16_bf16 v[66:81], v[178:181], v[162:165], v[66:81]
	v_exp_f32_e32 v85, v85
	v_exp_f32_e32 v117, v117
	ds_read_b64_tr_b16 v[110:111], v16 offset:12800
	ds_read_b64_tr_b16 v[112:113], v16 offset:13056
	s_waitcnt lgkmcnt(6)
	v_mfma_f32_32x32x16_bf16 v[50:65], v[4:7], v[98:101], v[50:65]
	v_exp_f32_e32 v86, v86
	v_exp_f32_e32 v118, v118
	ds_read_b64_tr_b16 v[130:131], v16 offset:1024
	ds_read_b64_tr_b16 v[132:133], v16 offset:1280
	s_waitcnt lgkmcnt(6)
	v_mfma_f32_32x32x16_bf16 v[50:65], v[8:11], v[102:105], v[50:65]
	v_exp_f32_e32 v87, v87
	v_exp_f32_e32 v119, v119
	ds_read_b64_tr_b16 v[134:135], v16 offset:5120
	ds_read_b64_tr_b16 v[136:137], v16 offset:5376
	s_waitcnt lgkmcnt(6)
	v_mfma_f32_32x32x16_bf16 v[50:65], v[12:15], v[106:109], v[50:65]
	v_exp_f32_e32 v88, v88
	v_exp_f32_e32 v120, v120
	ds_read_b64_tr_b16 v[138:139], v16 offset:9216
	ds_read_b64_tr_b16 v[140:141], v16 offset:9472
	s_waitcnt lgkmcnt(6)
	v_mfma_f32_32x32x16_bf16 v[50:65], v[178:181], v[110:113], v[50:65]
	v_exp_f32_e32 v89, v89
	v_exp_f32_e32 v121, v121
	ds_read_b64_tr_b16 v[142:143], v16 offset:13312
	ds_read_b64_tr_b16 v[144:145], v16 offset:13568
	s_waitcnt lgkmcnt(6)
	v_mfma_f32_32x32x16_bf16 v[34:49], v[4:7], v[130:133], v[34:49]
	v_exp_f32_e32 v90, v90
	v_exp_f32_e32 v122, v122
	ds_read_b64_tr_b16 v[98:99], v16 offset:1536
	ds_read_b64_tr_b16 v[100:101], v16 offset:1792
	s_waitcnt lgkmcnt(6)
	v_mfma_f32_32x32x16_bf16 v[34:49], v[8:11], v[134:137], v[34:49]
	v_exp_f32_e32 v91, v91
	v_exp_f32_e32 v123, v123
	ds_read_b64_tr_b16 v[102:103], v16 offset:5632
	ds_read_b64_tr_b16 v[104:105], v16 offset:5888
	s_waitcnt lgkmcnt(6)
	v_mfma_f32_32x32x16_bf16 v[34:49], v[12:15], v[138:141], v[34:49]
	v_exp_f32_e32 v92, v92
	v_exp_f32_e32 v124, v124
	ds_read_b64_tr_b16 v[106:107], v16 offset:9728
	ds_read_b64_tr_b16 v[108:109], v16 offset:9984
	s_waitcnt lgkmcnt(6)
	v_mfma_f32_32x32x16_bf16 v[34:49], v[178:181], v[142:145], v[34:49]
	v_exp_f32_e32 v93, v93
	v_exp_f32_e32 v125, v125
	ds_read_b64_tr_b16 v[110:111], v16 offset:13824
	ds_read_b64_tr_b16 v[112:113], v16 offset:14080
	s_waitcnt vmcnt(3)
	v_lshl_add_u32 v182, s86, 13, v215
	s_waitcnt lgkmcnt(0)
	s_barrier
; #define SBAR() __builtin_amdgcn_sched_barrier(0)
; template <int VAR> ...
;     ...
;     float ps = 0.f;
;     if constexpr (VAR & 4) { ka[0] = qr[0]; ka[1] = qr[1]; ka[2] = qr[2]; ka[3] = qr[3]; kb[0] = qr[0]; kb[1] = qr[1]; kb[2] = qr[2]; kb[3] = qr[3]; }
;     ka[0] = kp[0]; kb[0] = kp[1]; ka[1] = kp[2]; kb[1] = kp[3]; if (dk) glds16(gk, lk); SBAR();
;     { const f32x16 z = f32x16{};
;       QKM(x0, ka[0], qr[0], z);  SUM4(y0, 0); PKA(y0, 0);       SBAR();
;       QKM(x1, kb[0], qr[0], z);  SUM4(y0, 4); PKB(y0, 4, pa0);  KRD(2); if (dv) glds16(gv, lv); SBAR(); }
;     QKM(x0, ka[1], qr[1], x0); SUM4(y0, 8); PKA(y0, 8);       SBAR();
;     QKM(x1, kb[1], qr[1], x1); SUM4(y0, 12); PKB(y0, 12, pa1); KRD(3); if (dv) glds16(gv + 8192, lv + 8192); SBAR();
;     QKM(x0, ka[2], qr[2], x0); SUM4(y1, 0); PKA(y1, 0);       SBAR();
;     QKM(x1, kb[2], qr[2], x1); SUM4(y1, 4); PKB(y1, 4, pa2);  SBAR();
;     QKM(x0, ka[3], qr[3], x0); SUM4(y1, 8); PKA(y1, 8);       SBAR();
;     QKM(x1, kb[3], qr[3], x1); SUM4(y1, 12); PKB(y1, 12, pa3); VRD(0); VRD(1); SBAR();
;     VRD(2); VRD(3); SBAR();
;     if (near) {
;         float tA[4], uA[4], tB[4], uB[4];
;     ...
;         TLD(tA, uA, 0); SBAR(); TLD(tB, uB, 1); SBAR();
;         asm volatile("s_nop 15\n\ts_nop 7" : "+v"(x0), "+v"(x1));
;         TAD(tA, uA, 0); SBAR(); TLD(tA, uA, 2); SBAR(); TAD(tB, uB, 1); SBAR(); TLD(tB, uB, 3); SBAR(); TAD(tA, uA, 2); SBAR(); TAD(tB, uB, 3);
;     ...
;     } else if (__builtin_expect(shift != 0.f, 0)) {
;         asm volatile("s_nop 15\n\ts_nop 7" : "+v"(x0), "+v"(x1));
; #pragma unroll
;         for (int r = 0; r < 16; ++r) { asm volatile("v_sub_f32 %0, %0, %1" : "+v"(x0[r]) : "v"(shift)); asm volatile("v_sub_f32 %0, %0, %1" : "+v"(x1[r]) : "v"(shift)); }
;     }
;     SBAR();
;     ...
;     GAPB(0, pa0); GAPB(1, pa1); GAPB(2, pa2); GAPB(3, pa3); GAPB(4, pa0); GAPB(5, pa1); GAPB(6, pa2); GAPB(7, pa3);
;     GAPB(8, pa0); GAPB(9, pa1); GAPB(10, pa2); GAPB(11, pa3);
;     if (wv == 3) asm volatile("s_waitcnt vmcnt(3)" ::: "memory"); else if (wv == 2) asm volatile("s_waitcnt vmcnt(2)" ::: "memory"); else asm volatile("s_waitcnt vmcnt(0)" ::: "memory");
;     asm volatile("s_waitcnt lgkmcnt(0)\n\ts_barrier" ::: "memory");
;     if (pre) { const char* a0_ = Kn + (((0 + hi) ^ sw) << 4); const char* a1_ = Kn + (((2 + hi) ^ sw) << 4);
	v_add_u32_e32 v16, v182, v216
	v_add_u32_e32 v17, v182, v217
	ds_read_b128 v[174:177], v16 offset:49152
	ds_read_b128 v[170:173], v16 offset:53248
	ds_read_b128 v[166:169], v17 offset:49152
	ds_read_b128 v[162:165], v17 offset:53248
	s_waitcnt lgkmcnt(10)
	v_mfma_f32_32x32x16_bf16 v[18:33], v[4:7], v[98:101], v[18:33]
	v_exp_f32_e32 v94, v94
	v_exp_f32_e32 v126, v126
	s_waitcnt lgkmcnt(8)
	v_mfma_f32_32x32x16_bf16 v[18:33], v[8:11], v[102:105], v[18:33]
	v_exp_f32_e32 v95, v95
	v_exp_f32_e32 v127, v127
	s_waitcnt lgkmcnt(6)
	v_mfma_f32_32x32x16_bf16 v[18:33], v[12:15], v[106:109], v[18:33]
	v_exp_f32_e32 v96, v96
	v_exp_f32_e32 v128, v128
	s_waitcnt lgkmcnt(4)
	v_mfma_f32_32x32x16_bf16 v[18:33], v[178:181], v[110:113], v[18:33]
	v_exp_f32_e32 v97, v97
	v_exp_f32_e32 v129, v129
	s_add_i32 s0, s86, 1
	s_cmp_lg_u32 s86, 2
	s_cselect_b32 s68, s0, 0
	s_lshl_b32 s1, s68, 14
	s_add_i32 s20, s20, 2
	s_add_i32 m0, s92, s88
	s_add_i32 s69, s1, s87
	global_load_lds_dwordx4 v[206:207], off
	v_lshl_add_u64 v[12:13], v[208:209], 0, s[26:27]
	s_waitcnt lgkmcnt(3)
	v_mfma_f32_32x32x16_bf16 v[130:145], v[174:177], v[146:149], 0
	v_add_f32_e32 v4, v82, v83
	v_add_f32_e32 v5, v84, v85
	v_add_f32_e32 v6, v4, v5
	v_cvt_pk_bf16_f32 v4, v82, v83
	v_cvt_pk_bf16_f32 v5, v84, v85
	v_add_f32_e32 v7, v86, v87
	v_add_f32_e32 v8, v88, v89
	s_waitcnt lgkmcnt(2)
	v_mfma_f32_32x32x16_bf16 v[98:113], v[170:173], v[146:149], 0
	v_add_f32_e32 v7, v7, v8
	v_add_f32_e32 v8, v7, v6
	v_cvt_pk_bf16_f32 v6, v86, v87
	v_cvt_pk_bf16_f32 v7, v88, v89
	v_add_u32_e32 v9, v182, v218
	s_mov_b32 m0, s69
	ds_read_b128 v[14:17], v9 offset:49152
	ds_read_b128 v[82:85], v9 offset:53248
	global_load_lds_dwordx4 v[12:13], off
	s_waitcnt lgkmcnt(3)
	v_mfma_f32_32x32x16_bf16 v[130:145], v[166:169], v[150:153], v[130:145]
	v_add_f32_e32 v9, v90, v91
	v_add_f32_e32 v10, v92, v93
	v_add_f32_e32 v9, v9, v10
	v_add_f32_e32 v10, v9, v8
	v_cvt_pk_bf16_f32 v8, v90, v91
	v_cvt_pk_bf16_f32 v9, v92, v93
	v_add_f32_e32 v11, v94, v95
	v_add_f32_e32 v86, v96, v97
	s_waitcnt lgkmcnt(2)
	v_mfma_f32_32x32x16_bf16 v[98:113], v[162:165], v[150:153], v[98:113]
	v_add_f32_e32 v11, v11, v86
	v_add_f32_e32 v178, v11, v10
	v_cvt_pk_bf16_f32 v10, v94, v95
	v_cvt_pk_bf16_f32 v11, v96, v97
	v_add_u32_e32 v86, v182, v219
	ds_read_b128 v[90:93], v86 offset:49152
	ds_read_b128 v[86:89], v86 offset:53248
	s_add_i32 m0, s69, 0x2000
	v_lshl_add_u64 v[12:13], v[12:13], 0, s[22:23]
	global_load_lds_dwordx4 v[12:13], off
	s_lshl_b32 s0, s91, 14
	s_cmp_le_i32 s89, s85
	s_waitcnt lgkmcnt(3)
	v_mfma_f32_32x32x16_bf16 v[130:145], v[14:17], v[154:157], v[130:145]
	v_add_f32_e32 v12, v114, v115
	v_add_f32_e32 v13, v116, v117
	v_add_f32_e32 v12, v12, v13
	v_add_f32_e32 v94, v12, v178
	v_cvt_pk_bf16_f32 v12, v114, v115
	v_cvt_pk_bf16_f32 v13, v116, v117
	s_waitcnt lgkmcnt(2)
	v_mfma_f32_32x32x16_bf16 v[98:113], v[82:85], v[154:157], v[98:113]
	v_add_f32_e32 v14, v118, v119
	v_add_f32_e32 v15, v120, v121
	v_add_f32_e32 v14, v14, v15
	v_add_f32_e32 v16, v14, v94
	v_cvt_pk_bf16_f32 v14, v118, v119
	v_cvt_pk_bf16_f32 v15, v120, v121
	s_waitcnt lgkmcnt(1)
	v_mfma_f32_32x32x16_bf16 v[130:145], v[90:93], v[158:161], v[130:145]
	v_add_f32_e32 v17, v122, v123
	v_add_f32_e32 v82, v124, v125
	v_add_f32_e32 v17, v17, v82
	v_add_f32_e32 v16, v17, v16
	v_cvt_pk_bf16_f32 v178, v122, v123
	v_cvt_pk_bf16_f32 v179, v124, v125
	v_add_f32_e32 v17, v126, v127
	v_add_f32_e32 v82, v128, v129
	v_add_f32_e32 v17, v17, v82
	v_add_f32_e32 v16, v17, v16
	v_cvt_pk_bf16_f32 v180, v126, v127
	v_cvt_pk_bf16_f32 v181, v128, v129
	v_add_u32_e32 v17, s0, v214
	s_waitcnt lgkmcnt(0)
	v_mfma_f32_32x32x16_bf16 v[98:113], v[86:89], v[158:161], v[98:113]
	ds_read_b64_tr_b16 v[194:195], v17
	ds_read_b64_tr_b16 v[196:197], v17 offset:256
	ds_read_b64_tr_b16 v[190:191], v17 offset:4096
	ds_read_b64_tr_b16 v[192:193], v17 offset:4352
	ds_read_b64_tr_b16 v[186:187], v17 offset:8192
	ds_read_b64_tr_b16 v[188:189], v17 offset:8448
	ds_read_b64_tr_b16 v[182:183], v17 offset:12288
	ds_read_b64_tr_b16 v[184:185], v17 offset:12544
	s_cbranch_scc0 .LBB0_398
	v_mov_b64_e32 v[82:83], v[130:131]
	s_and_b64 vcc, exec, s[4:5]
	v_mov_b64_e32 v[84:85], v[132:133]
	v_mov_b64_e32 v[86:87], v[134:135]
	v_mov_b64_e32 v[88:89], v[136:137]
	v_mov_b64_e32 v[90:91], v[138:139]
	v_mov_b64_e32 v[92:93], v[140:141]
	v_mov_b64_e32 v[94:95], v[142:143]
	v_mov_b64_e32 v[96:97], v[144:145]
	s_cbranch_vccnz .Lp2t_shift2

; #define SBAR() __builtin_amdgcn_sched_barrier(0)
; #define TLD(T, U, g) do { _Pragma("unroll") for (int j = 0; j < 4; ++j) { const int r_ = 4 * (g) + j, c_ = (r_ & 3) + 8 * (r_ >> 2); T[j] = *(const float*)(tabp + 4 * (59 - c_)); U[j] = *(const float*)(tabp + 4 * (59 - c_ - 32)); } } while (0)
; #define TAD(T, U, g) do { _Pragma("unroll") for (int j = 0; j < 4; ++j) { const int r_ = 4 * (g) + j; asm volatile("v_add_f32 %0, %0, %1" : "+v"(x0[r_]) : "v"(T[j])); asm volatile("v_add_f32 %0, %0, %1" : "+v"(x1[r_]) : "v"(U[j])); } } while (0)
; template <int VAR> ...
;     ...
;     if (near) {
;         float tA[4], uA[4], tB[4], uB[4];
;     ...
;         TLD(tA, uA, 0); SBAR(); TLD(tB, uB, 1); SBAR();
;         asm volatile("s_nop 15\n\ts_nop 7" : "+v"(x0), "+v"(x1));
;         TAD(tA, uA, 0); SBAR(); TLD(tA, uA, 2); SBAR(); TAD(tB, uB, 1); SBAR(); TLD(tB, uB, 3); SBAR(); TAD(tA, uA, 2); SBAR(); TAD(tB, uB, 3);
.LBB0_397:
	ds_read2_b32 v[82:83], v3 offset0:123 offset1:122
	ds_read2_b32 v[84:85], v3 offset0:121 offset1:120
	ds_read2_b32 v[86:87], v3 offset0:115 offset1:114
	ds_read2_b32 v[88:89], v3 offset0:113 offset1:112
	ds_read2_b32 v[90:91], v3 offset0:107 offset1:106
	ds_read2_b32 v[92:93], v3 offset0:105 offset1:104
	ds_read2_b32 v[94:95], v3 offset0:99 offset1:98
	ds_read2_b32 v[96:97], v3 offset0:97 offset1:96
	s_waitcnt lgkmcnt(8)
	ds_read2_b32 v[98:99], v3 offset0:91 offset1:90
	ds_read2_b32 v[100:101], v3 offset0:89 offset1:88
	ds_read2_b32 v[102:103], v3 offset0:83 offset1:82
	ds_read2_b32 v[104:105], v3 offset0:81 offset1:80
	ds_read2_b32 v[106:107], v3 offset0:75 offset1:74
	ds_read2_b32 v[108:109], v3 offset0:73 offset1:72
	ds_read2_b32 v[110:111], v3 offset0:67 offset1:66
	ds_read2_b32 v[112:113], v3 offset0:65 offset1:64
	s_waitcnt lgkmcnt(8)
	v_add_f32_e32 v82, v130, v82
	v_add_f32_e32 v83, v131, v83
	v_add_f32_e32 v84, v132, v84
	v_add_f32_e32 v85, v133, v85
	v_add_f32_e32 v86, v134, v86
	v_add_f32_e32 v87, v135, v87
	v_add_f32_e32 v88, v136, v88
	v_add_f32_e32 v89, v137, v89
	v_add_f32_e32 v90, v138, v90
	v_add_f32_e32 v91, v139, v91
	v_add_f32_e32 v92, v140, v92
	v_add_f32_e32 v93, v141, v93
	v_add_f32_e32 v94, v142, v94
	v_add_f32_e32 v95, v143, v95
	v_add_f32_e32 v96, v144, v96
	v_add_f32_e32 v97, v145, v97
	s_waitcnt lgkmcnt(0)
	v_add_f32_e32 v114, v114, v98
	v_add_f32_e32 v115, v115, v99
	v_add_f32_e32 v116, v116, v100
	v_add_f32_e32 v117, v117, v101
	v_add_f32_e32 v118, v118, v102
	v_add_f32_e32 v119, v119, v103
	v_add_f32_e32 v120, v120, v104
	v_add_f32_e32 v121, v121, v105
	v_add_f32_e32 v122, v122, v106
	v_add_f32_e32 v123, v123, v107
	v_add_f32_e32 v124, v124, v108
	v_add_f32_e32 v125, v125, v109
	v_add_f32_e32 v126, v126, v110
	v_add_f32_e32 v127, v127, v111
	v_add_f32_e32 v128, v128, v112
	v_add_f32_e32 v129, v129, v113
	s_branch .LBB0_367

; #define SBAR() __builtin_amdgcn_sched_barrier(0)
; #define TLD(T, U, g) do { _Pragma("unroll") for (int j = 0; j < 4; ++j) { const int r_ = 4 * (g) + j, c_ = (r_ & 3) + 8 * (r_ >> 2); T[j] = *(const float*)(tabp + 4 * (59 - c_)); U[j] = *(const float*)(tabp + 4 * (59 - c_ - 32)); } } while (0)
; #define TAD(T, U, g) do { _Pragma("unroll") for (int j = 0; j < 4; ++j) { const int r_ = 4 * (g) + j; asm volatile("v_add_f32 %0, %0, %1" : "+v"(x0[r_]) : "v"(T[j])); asm volatile("v_add_f32 %0, %0, %1" : "+v"(x1[r_]) : "v"(U[j])); } } while (0)
; template <int VAR> ...
;     ...
;     if (near) {
;         float tA[4], uA[4], tB[4], uB[4];
;     ...
;         TLD(tA, uA, 0); SBAR(); TLD(tB, uB, 1); SBAR();
;         asm volatile("s_nop 15\n\ts_nop 7" : "+v"(x0), "+v"(x1));
;         TAD(tA, uA, 0); SBAR(); TLD(tA, uA, 2); SBAR(); TAD(tB, uB, 1); SBAR(); TLD(tB, uB, 3); SBAR(); TAD(tA, uA, 2); SBAR(); TAD(tB, uB, 3);
.LBB0_399:
	ds_read2_b32 v[82:83], v3 offset0:59 offset1:58
	ds_read2_b32 v[84:85], v3 offset0:57 offset1:56
	ds_read2_b32 v[86:87], v3 offset0:51 offset1:50
	ds_read2_b32 v[88:89], v3 offset0:49 offset1:48
	ds_read2_b32 v[90:91], v3 offset0:43 offset1:42
	ds_read2_b32 v[92:93], v3 offset0:41 offset1:40
	ds_read2_b32 v[94:95], v3 offset0:35 offset1:34
	ds_read2_b32 v[96:97], v3 offset0:33 offset1:32
	s_waitcnt lgkmcnt(8)
	ds_read2_b32 v[114:115], v3 offset0:27 offset1:26
	ds_read2_b32 v[116:117], v3 offset0:25 offset1:24
	ds_read2_b32 v[118:119], v3 offset0:19 offset1:18
	ds_read2_b32 v[120:121], v3 offset0:17 offset1:16
	ds_read2_b32 v[122:123], v3 offset0:11 offset1:10
	ds_read2_b32 v[124:125], v3 offset0:9 offset1:8
	ds_read2_b32 v[126:127], v3 offset0:3 offset1:2
	ds_read2_b32 v[128:129], v3 offset0:1 offset1:0
	s_waitcnt lgkmcnt(8)
	v_add_f32_e32 v82, v130, v82
	v_add_f32_e32 v83, v131, v83
	v_add_f32_e32 v84, v132, v84
	v_add_f32_e32 v85, v133, v85
	v_add_f32_e32 v86, v134, v86
	v_add_f32_e32 v87, v135, v87
	v_add_f32_e32 v88, v136, v88
	v_add_f32_e32 v89, v137, v89
	v_add_f32_e32 v90, v138, v90
	v_add_f32_e32 v91, v139, v91
	v_add_f32_e32 v92, v140, v92
	v_add_f32_e32 v93, v141, v93
	v_add_f32_e32 v94, v142, v94
	v_add_f32_e32 v95, v143, v95
	v_add_f32_e32 v96, v144, v96
	v_add_f32_e32 v97, v145, v97
	s_waitcnt lgkmcnt(0)
	v_add_f32_e32 v98, v98, v114
	v_add_f32_e32 v99, v99, v115
	v_add_f32_e32 v100, v100, v116
	v_add_f32_e32 v101, v101, v117
	v_add_f32_e32 v102, v102, v118
	v_add_f32_e32 v103, v103, v119
	v_add_f32_e32 v104, v104, v120
	v_add_f32_e32 v105, v105, v121
	v_add_f32_e32 v106, v106, v122
	v_add_f32_e32 v107, v107, v123
	v_add_f32_e32 v108, v108, v124
	v_add_f32_e32 v109, v109, v125
	v_add_f32_e32 v110, v110, v126
	v_add_f32_e32 v111, v111, v127
	v_add_f32_e32 v112, v112, v128
	v_add_f32_e32 v113, v113, v129
	s_branch .LBB0_385
